# down-projection L1 epilogue: residual / row-sum stores marked nt (less dirty L2 to write back at the last grid barrier)
# baseline (speedup 1.0000x reference)
.LBB0_1464:
	v_lshl_add_u32 v146, s42, 8, v148
	v_ashrrev_i32_e32 v147, 31, v146
	v_lshl_or_b32 v144, s8, 8, v150
	v_lshlrev_b64 v[156:157], 11, v[146:147]
	v_ashrrev_i32_e32 v145, 31, v144
	v_lshl_add_u64 v[156:157], s[74:75], 0, v[156:157]
	v_lshl_add_u64 v[166:167], v[144:145], 1, v[156:157]
	global_load_dwordx4 v[158:161], v[166:167], off
	global_load_dwordx4 v[162:165], v[166:167], off offset:256
	v_and_b32_e32 v156, 64, v154
	v_xor_b32_e32 v155, 16, v154
	v_add_u32_e32 v156, 64, v156
	v_xor_b32_e32 v157, 32, v154
	v_cmp_lt_i32_e32 vcc, v155, v156
	s_lshl_b32 s18, s8, 2
	s_ashr_i32 s19, s18, 31
	v_cndmask_b32_e32 v155, v154, v155, vcc
	v_cmp_lt_i32_e32 vcc, v157, v156
	v_lshlrev_b32_e32 v156, 2, v155
	s_waitcnt vmcnt(0)
	v_lshlrev_b32_e32 v168, 16, v158
	v_and_b32_e32 v169, 0xffff0000, v158
	v_lshlrev_b32_e32 v158, 16, v159
	v_and_b32_e32 v159, 0xffff0000, v159
	v_lshlrev_b32_e32 v170, 16, v160
	v_and_b32_e32 v171, 0xffff0000, v160
	v_lshlrev_b32_e32 v160, 16, v161
	v_and_b32_e32 v161, 0xffff0000, v161
	v_lshlrev_b32_e32 v172, 16, v162
	v_and_b32_e32 v173, 0xffff0000, v162
	v_lshlrev_b32_e32 v162, 16, v163
	v_and_b32_e32 v163, 0xffff0000, v163
	v_lshlrev_b32_e32 v174, 16, v164
	v_and_b32_e32 v175, 0xffff0000, v164
	v_lshlrev_b32_e32 v164, 16, v165
	v_and_b32_e32 v165, 0xffff0000, v165
	v_cndmask_b32_e32 v157, v154, v157, vcc
	v_pk_add_f32 v[126:127], v[126:127], v[158:159]
	v_pk_add_f32 v[124:125], v[124:125], v[168:169]
	v_pk_add_f32 v[122:123], v[122:123], v[160:161]
	v_pk_add_f32 v[120:121], v[120:121], v[170:171]
	v_pk_add_f32 v[118:119], v[118:119], v[162:163]
	v_pk_add_f32 v[116:117], v[116:117], v[172:173]
	v_pk_add_f32 v[158:159], v[114:115], v[164:165]
	v_pk_add_f32 v[160:161], v[112:113], v[174:175]
	v_lshlrev_b32_e32 v155, 2, v157
	v_cvt_pk_bf16_f32 v112, v124, v125
	v_cvt_pk_bf16_f32 v113, v126, v127
	v_mul_f32_e32 v114, v125, v125
	v_mul_f32_e32 v115, v127, v127
	v_mul_f32_e32 v125, v121, v121
	v_mul_f32_e32 v127, v123, v123
	v_mul_f32_e32 v157, v117, v117
	v_mul_f32_e32 v162, v119, v119
	v_mul_f32_e32 v163, v161, v161
	v_mul_f32_e32 v164, v159, v159
	v_fmac_f32_e32 v114, v124, v124
	v_fmac_f32_e32 v115, v126, v126
	v_fmac_f32_e32 v125, v120, v120
	v_fmac_f32_e32 v127, v122, v122
	v_fmac_f32_e32 v157, v116, v116
	v_fmac_f32_e32 v162, v118, v118
	v_fmac_f32_e32 v163, v160, v160
	v_fmac_f32_e32 v164, v158, v158
	v_add_f32_e32 v114, v114, v115
	v_add_f32_e32 v115, v125, v127
	v_add_f32_e32 v124, v157, v162
	v_add_f32_e32 v125, v163, v164
	v_add_f32_e32 v114, v114, v115
	v_add_f32_e32 v115, v124, v125
	v_add_f32_e32 v124, v114, v115
	ds_bpermute_b32 v125, v156, v124
	v_cvt_pk_bf16_f32 v114, v120, v121
	v_cvt_pk_bf16_f32 v115, v122, v123
	global_store_dwordx4 v[166:167], v[112:115], off nt
	s_waitcnt lgkmcnt(0)
	s_nop 0
	v_add_f32_e32 v112, v124, v125
	ds_bpermute_b32 v113, v155, v112
	v_cvt_pk_bf16_f32 v114, v116, v117
	v_cvt_pk_bf16_f32 v115, v118, v119
	v_cvt_pk_bf16_f32 v116, v160, v161
	v_cvt_pk_bf16_f32 v117, v158, v159
	global_store_dwordx4 v[166:167], v[114:117], off offset:256 nt
	s_and_saveexec_b64 s[20:21], s[0:1]
	s_cbranch_execz .LBB0_1466
	v_lshlrev_b64 v[114:115], 6, v[146:147]
	v_lshl_add_u64 v[114:115], s[68:69], 0, v[114:115]
	v_lshl_add_u64 v[114:115], s[18:19], 2, v[114:115]
	s_lshl_b32 s8, s34, 2
	v_lshl_add_u64 v[114:115], v[114:115], 0, s[8:9]
	s_waitcnt lgkmcnt(0)
	v_add_f32_e32 v112, v112, v113
	global_store_dword v[114:115], v112, off nt
.LBB0_1466:
	s_or_b64 exec, exec, s[20:21]
	v_or_b32_e32 v112, 16, v146
	s_waitcnt lgkmcnt(0)
	v_ashrrev_i32_e32 v113, 31, v112
	v_lshlrev_b64 v[114:115], 11, v[112:113]
	v_lshl_add_u64 v[114:115], s[74:75], 0, v[114:115]
	v_lshl_add_u64 v[122:123], v[144:145], 1, v[114:115]
	global_load_dwordx4 v[114:117], v[122:123], off
	global_load_dwordx4 v[118:121], v[122:123], off offset:256
	s_waitcnt vmcnt(1)
	v_lshlrev_b32_e32 v124, 16, v114
	v_and_b32_e32 v125, 0xffff0000, v114
	v_lshlrev_b32_e32 v114, 16, v115
	v_and_b32_e32 v115, 0xffff0000, v115
	v_lshlrev_b32_e32 v126, 16, v116
	v_and_b32_e32 v127, 0xffff0000, v116
	v_lshlrev_b32_e32 v116, 16, v117
	v_and_b32_e32 v117, 0xffff0000, v117
	s_waitcnt vmcnt(0)
	v_lshlrev_b32_e32 v158, 16, v118
	v_and_b32_e32 v159, 0xffff0000, v118
	v_lshlrev_b32_e32 v118, 16, v119
	v_and_b32_e32 v119, 0xffff0000, v119
	v_lshlrev_b32_e32 v160, 16, v120
	v_and_b32_e32 v161, 0xffff0000, v120
	v_lshlrev_b32_e32 v120, 16, v121
	v_and_b32_e32 v121, 0xffff0000, v121
	v_pk_add_f32 v[110:111], v[110:111], v[114:115]
	v_pk_add_f32 v[108:109], v[108:109], v[124:125]
	v_pk_add_f32 v[106:107], v[106:107], v[116:117]
	v_pk_add_f32 v[104:105], v[104:105], v[126:127]
	v_pk_add_f32 v[102:103], v[102:103], v[118:119]
	v_pk_add_f32 v[100:101], v[100:101], v[158:159]
	v_pk_add_f32 v[114:115], v[98:99], v[120:121]
	v_pk_add_f32 v[116:117], v[96:97], v[160:161]
	v_cvt_pk_bf16_f32 v96, v108, v109
	v_cvt_pk_bf16_f32 v97, v110, v111
	v_mul_f32_e32 v98, v109, v109
	v_mul_f32_e32 v99, v111, v111
	v_mul_f32_e32 v109, v105, v105
	v_mul_f32_e32 v111, v107, v107
	v_mul_f32_e32 v118, v101, v101
	v_mul_f32_e32 v119, v103, v103
	v_mul_f32_e32 v120, v117, v117
	v_mul_f32_e32 v121, v115, v115
	v_fmac_f32_e32 v98, v108, v108
	v_fmac_f32_e32 v99, v110, v110
	v_fmac_f32_e32 v109, v104, v104
	v_fmac_f32_e32 v111, v106, v106
	v_fmac_f32_e32 v118, v100, v100
	v_fmac_f32_e32 v119, v102, v102
	v_fmac_f32_e32 v120, v116, v116
	v_fmac_f32_e32 v121, v114, v114
	v_add_f32_e32 v98, v98, v99
	v_add_f32_e32 v99, v109, v111
	v_add_f32_e32 v108, v118, v119
	v_add_f32_e32 v109, v120, v121
	v_add_f32_e32 v98, v98, v99
	v_add_f32_e32 v99, v108, v109
	v_add_f32_e32 v108, v98, v99
	ds_bpermute_b32 v109, v156, v108
	v_cvt_pk_bf16_f32 v98, v104, v105
	v_cvt_pk_bf16_f32 v99, v106, v107
	global_store_dwordx4 v[122:123], v[96:99], off nt
	s_waitcnt lgkmcnt(0)
	s_nop 0
	v_add_f32_e32 v96, v108, v109
	ds_bpermute_b32 v97, v155, v96
	v_cvt_pk_bf16_f32 v98, v100, v101
	v_cvt_pk_bf16_f32 v99, v102, v103
	v_cvt_pk_bf16_f32 v100, v116, v117
	v_cvt_pk_bf16_f32 v101, v114, v115
	global_store_dwordx4 v[122:123], v[98:101], off offset:256 nt
	s_and_saveexec_b64 s[20:21], s[0:1]
	s_cbranch_execz .LBB0_1468
	v_lshlrev_b64 v[98:99], 6, v[112:113]
	v_lshl_add_u64 v[98:99], s[68:69], 0, v[98:99]
	v_lshl_add_u64 v[98:99], s[18:19], 2, v[98:99]
	s_lshl_b32 s8, s34, 2
	v_lshl_add_u64 v[98:99], v[98:99], 0, s[8:9]
	s_waitcnt lgkmcnt(0)
	v_add_f32_e32 v96, v96, v97
	global_store_dword v[98:99], v96, off nt
.LBB0_1468:
	s_or_b64 exec, exec, s[20:21]
	v_or_b32_e32 v96, 32, v146
	s_waitcnt lgkmcnt(0)
	v_ashrrev_i32_e32 v97, 31, v96
	v_lshlrev_b64 v[98:99], 11, v[96:97]
	v_lshl_add_u64 v[98:99], s[74:75], 0, v[98:99]
	v_lshl_add_u64 v[106:107], v[144:145], 1, v[98:99]
	global_load_dwordx4 v[98:101], v[106:107], off
	global_load_dwordx4 v[102:105], v[106:107], off offset:256
	s_waitcnt vmcnt(1)
	v_lshlrev_b32_e32 v108, 16, v98
	v_and_b32_e32 v109, 0xffff0000, v98
	v_lshlrev_b32_e32 v98, 16, v99
	v_and_b32_e32 v99, 0xffff0000, v99
	v_lshlrev_b32_e32 v110, 16, v100
	v_and_b32_e32 v111, 0xffff0000, v100
	v_lshlrev_b32_e32 v100, 16, v101
	v_and_b32_e32 v101, 0xffff0000, v101
	s_waitcnt vmcnt(0)
	v_lshlrev_b32_e32 v112, 16, v102
	v_and_b32_e32 v113, 0xffff0000, v102
	v_lshlrev_b32_e32 v102, 16, v103
	v_and_b32_e32 v103, 0xffff0000, v103
	v_lshlrev_b32_e32 v114, 16, v104
	v_and_b32_e32 v115, 0xffff0000, v104
	v_lshlrev_b32_e32 v104, 16, v105
	v_and_b32_e32 v105, 0xffff0000, v105
	v_pk_add_f32 v[94:95], v[94:95], v[98:99]
	v_pk_add_f32 v[92:93], v[92:93], v[108:109]
	v_pk_add_f32 v[90:91], v[90:91], v[100:101]
	v_pk_add_f32 v[88:89], v[88:89], v[110:111]
	v_pk_add_f32 v[86:87], v[86:87], v[102:103]
	v_pk_add_f32 v[84:85], v[84:85], v[112:113]
	v_pk_add_f32 v[98:99], v[82:83], v[104:105]
	v_pk_add_f32 v[100:101], v[80:81], v[114:115]
	v_cvt_pk_bf16_f32 v80, v92, v93
	v_cvt_pk_bf16_f32 v81, v94, v95
	v_mul_f32_e32 v82, v93, v93
	v_mul_f32_e32 v83, v95, v95
	v_mul_f32_e32 v93, v89, v89
	v_mul_f32_e32 v95, v91, v91
	v_mul_f32_e32 v102, v85, v85
	v_mul_f32_e32 v103, v87, v87
	v_mul_f32_e32 v104, v101, v101
	v_mul_f32_e32 v105, v99, v99
	v_fmac_f32_e32 v82, v92, v92
	v_fmac_f32_e32 v83, v94, v94
	v_fmac_f32_e32 v93, v88, v88
	v_fmac_f32_e32 v95, v90, v90
	v_fmac_f32_e32 v102, v84, v84
	v_fmac_f32_e32 v103, v86, v86
	v_fmac_f32_e32 v104, v100, v100
	v_fmac_f32_e32 v105, v98, v98
	v_add_f32_e32 v82, v82, v83
	v_add_f32_e32 v83, v93, v95
	v_add_f32_e32 v92, v102, v103
	v_add_f32_e32 v93, v104, v105
	v_add_f32_e32 v82, v82, v83
	v_add_f32_e32 v83, v92, v93
	v_add_f32_e32 v92, v82, v83
	ds_bpermute_b32 v93, v156, v92
	v_cvt_pk_bf16_f32 v82, v88, v89
	v_cvt_pk_bf16_f32 v83, v90, v91
	global_store_dwordx4 v[106:107], v[80:83], off nt
	s_waitcnt lgkmcnt(0)
	s_nop 0
	v_add_f32_e32 v80, v92, v93
	ds_bpermute_b32 v81, v155, v80
	v_cvt_pk_bf16_f32 v82, v84, v85
	v_cvt_pk_bf16_f32 v83, v86, v87
	v_cvt_pk_bf16_f32 v84, v100, v101
	v_cvt_pk_bf16_f32 v85, v98, v99
	global_store_dwordx4 v[106:107], v[82:85], off offset:256 nt
	s_and_saveexec_b64 s[20:21], s[0:1]
	s_cbranch_execz .LBB0_1470
	v_lshlrev_b64 v[82:83], 6, v[96:97]
	v_lshl_add_u64 v[82:83], s[68:69], 0, v[82:83]
	v_lshl_add_u64 v[82:83], s[18:19], 2, v[82:83]
	s_lshl_b32 s8, s34, 2
	v_lshl_add_u64 v[82:83], v[82:83], 0, s[8:9]
	s_waitcnt lgkmcnt(0)
	v_add_f32_e32 v80, v80, v81
	global_store_dword v[82:83], v80, off nt
.LBB0_1470:
	s_or_b64 exec, exec, s[20:21]
	v_or_b32_e32 v80, 48, v146
	s_waitcnt lgkmcnt(0)
	v_ashrrev_i32_e32 v81, 31, v80
	v_lshlrev_b64 v[82:83], 11, v[80:81]
	v_lshl_add_u64 v[82:83], s[74:75], 0, v[82:83]
	v_lshl_add_u64 v[90:91], v[144:145], 1, v[82:83]
	global_load_dwordx4 v[82:85], v[90:91], off
	global_load_dwordx4 v[86:89], v[90:91], off offset:256
	s_waitcnt vmcnt(1)
	v_lshlrev_b32_e32 v92, 16, v82
	v_and_b32_e32 v93, 0xffff0000, v82
	v_lshlrev_b32_e32 v82, 16, v83
	v_and_b32_e32 v83, 0xffff0000, v83
	v_lshlrev_b32_e32 v94, 16, v84
	v_and_b32_e32 v95, 0xffff0000, v84
	v_lshlrev_b32_e32 v84, 16, v85
	v_and_b32_e32 v85, 0xffff0000, v85
	s_waitcnt vmcnt(0)
	v_lshlrev_b32_e32 v96, 16, v86
	v_and_b32_e32 v97, 0xffff0000, v86
	v_lshlrev_b32_e32 v86, 16, v87
	v_and_b32_e32 v87, 0xffff0000, v87
	v_lshlrev_b32_e32 v98, 16, v88
	v_and_b32_e32 v99, 0xffff0000, v88
	v_lshlrev_b32_e32 v88, 16, v89
	v_and_b32_e32 v89, 0xffff0000, v89
	v_pk_add_f32 v[78:79], v[78:79], v[82:83]
	v_pk_add_f32 v[76:77], v[76:77], v[92:93]
	v_pk_add_f32 v[74:75], v[74:75], v[84:85]
	v_pk_add_f32 v[72:73], v[72:73], v[94:95]
	v_pk_add_f32 v[70:71], v[70:71], v[86:87]
	v_pk_add_f32 v[68:69], v[68:69], v[96:97]
	v_pk_add_f32 v[82:83], v[66:67], v[88:89]
	v_pk_add_f32 v[84:85], v[64:65], v[98:99]
	v_cvt_pk_bf16_f32 v64, v76, v77
	v_cvt_pk_bf16_f32 v65, v78, v79
	v_mul_f32_e32 v66, v77, v77
	v_mul_f32_e32 v67, v79, v79
	v_mul_f32_e32 v77, v73, v73
	v_mul_f32_e32 v79, v75, v75
	v_mul_f32_e32 v86, v69, v69
	v_mul_f32_e32 v87, v71, v71
	v_mul_f32_e32 v88, v85, v85
	v_mul_f32_e32 v89, v83, v83
	v_fmac_f32_e32 v66, v76, v76
	v_fmac_f32_e32 v67, v78, v78
	v_fmac_f32_e32 v77, v72, v72
	v_fmac_f32_e32 v79, v74, v74
	v_fmac_f32_e32 v86, v68, v68
	v_fmac_f32_e32 v87, v70, v70
	v_fmac_f32_e32 v88, v84, v84
	v_fmac_f32_e32 v89, v82, v82
	v_add_f32_e32 v66, v66, v67
	v_add_f32_e32 v67, v77, v79
	v_add_f32_e32 v76, v86, v87
	v_add_f32_e32 v77, v88, v89
	v_add_f32_e32 v66, v66, v67
	v_add_f32_e32 v67, v76, v77
	v_add_f32_e32 v76, v66, v67
	ds_bpermute_b32 v77, v156, v76
	v_cvt_pk_bf16_f32 v66, v72, v73
	v_cvt_pk_bf16_f32 v67, v74, v75
	global_store_dwordx4 v[90:91], v[64:67], off nt
	s_waitcnt lgkmcnt(0)
	s_nop 0
	v_add_f32_e32 v64, v76, v77
	ds_bpermute_b32 v65, v155, v64
	v_cvt_pk_bf16_f32 v66, v68, v69
	v_cvt_pk_bf16_f32 v67, v70, v71
	v_cvt_pk_bf16_f32 v68, v84, v85
	v_cvt_pk_bf16_f32 v69, v82, v83
	global_store_dwordx4 v[90:91], v[66:69], off offset:256 nt
	s_and_saveexec_b64 s[20:21], s[0:1]
	s_cbranch_execz .LBB0_1472
	v_lshlrev_b64 v[66:67], 6, v[80:81]
	v_lshl_add_u64 v[66:67], s[68:69], 0, v[66:67]
	v_lshl_add_u64 v[66:67], s[18:19], 2, v[66:67]
	s_lshl_b32 s8, s34, 2
	v_lshl_add_u64 v[66:67], v[66:67], 0, s[8:9]
	s_waitcnt lgkmcnt(0)
	v_add_f32_e32 v64, v64, v65
	global_store_dword v[66:67], v64, off nt
.LBB0_1472:
	s_or_b64 exec, exec, s[20:21]
	v_add_u32_e32 v64, 0x80, v146
	s_waitcnt lgkmcnt(0)
	v_ashrrev_i32_e32 v65, 31, v64
	v_lshlrev_b64 v[66:67], 11, v[64:65]
	v_lshl_add_u64 v[66:67], s[74:75], 0, v[66:67]
	v_lshl_add_u64 v[74:75], v[144:145], 1, v[66:67]
	global_load_dwordx4 v[66:69], v[74:75], off
	global_load_dwordx4 v[70:73], v[74:75], off offset:256
	s_waitcnt vmcnt(1)
	v_lshlrev_b32_e32 v76, 16, v66
	v_and_b32_e32 v77, 0xffff0000, v66
	v_lshlrev_b32_e32 v66, 16, v67
	v_and_b32_e32 v67, 0xffff0000, v67
	v_lshlrev_b32_e32 v78, 16, v68
	v_and_b32_e32 v79, 0xffff0000, v68
	v_lshlrev_b32_e32 v68, 16, v69
	v_and_b32_e32 v69, 0xffff0000, v69
	s_waitcnt vmcnt(0)
	v_lshlrev_b32_e32 v80, 16, v70
	v_and_b32_e32 v81, 0xffff0000, v70
	v_lshlrev_b32_e32 v70, 16, v71
	v_and_b32_e32 v71, 0xffff0000, v71
	v_lshlrev_b32_e32 v82, 16, v72
	v_and_b32_e32 v83, 0xffff0000, v72
	v_lshlrev_b32_e32 v72, 16, v73
	v_and_b32_e32 v73, 0xffff0000, v73
	v_pk_add_f32 v[62:63], v[62:63], v[66:67]
	v_pk_add_f32 v[60:61], v[60:61], v[76:77]
	v_pk_add_f32 v[58:59], v[58:59], v[68:69]
	v_pk_add_f32 v[56:57], v[56:57], v[78:79]
	v_pk_add_f32 v[54:55], v[54:55], v[70:71]
	v_pk_add_f32 v[52:53], v[52:53], v[80:81]
	v_pk_add_f32 v[66:67], v[50:51], v[72:73]
	v_pk_add_f32 v[68:69], v[48:49], v[82:83]
	v_cvt_pk_bf16_f32 v48, v60, v61
	v_cvt_pk_bf16_f32 v49, v62, v63
	v_mul_f32_e32 v50, v61, v61
	v_mul_f32_e32 v51, v63, v63
	v_mul_f32_e32 v61, v57, v57
	v_mul_f32_e32 v63, v59, v59
	v_mul_f32_e32 v70, v53, v53
	v_mul_f32_e32 v71, v55, v55
	v_mul_f32_e32 v72, v69, v69
	v_mul_f32_e32 v73, v67, v67
	v_fmac_f32_e32 v50, v60, v60
	v_fmac_f32_e32 v51, v62, v62
	v_fmac_f32_e32 v61, v56, v56
	v_fmac_f32_e32 v63, v58, v58
	v_fmac_f32_e32 v70, v52, v52
	v_fmac_f32_e32 v71, v54, v54
	v_fmac_f32_e32 v72, v68, v68
	v_fmac_f32_e32 v73, v66, v66
	v_add_f32_e32 v50, v50, v51
	v_add_f32_e32 v51, v61, v63
	v_add_f32_e32 v60, v70, v71
	v_add_f32_e32 v61, v72, v73
	v_add_f32_e32 v50, v50, v51
	v_add_f32_e32 v51, v60, v61
	v_add_f32_e32 v60, v50, v51
	ds_bpermute_b32 v61, v156, v60
	v_cvt_pk_bf16_f32 v50, v56, v57
	v_cvt_pk_bf16_f32 v51, v58, v59
	global_store_dwordx4 v[74:75], v[48:51], off nt
	s_waitcnt lgkmcnt(0)
	s_nop 0
	v_add_f32_e32 v48, v60, v61
	ds_bpermute_b32 v49, v155, v48
	v_cvt_pk_bf16_f32 v50, v52, v53
	v_cvt_pk_bf16_f32 v51, v54, v55
	v_cvt_pk_bf16_f32 v52, v68, v69
	v_cvt_pk_bf16_f32 v53, v66, v67
	global_store_dwordx4 v[74:75], v[50:53], off offset:256 nt
	s_and_saveexec_b64 s[20:21], s[0:1]
	s_cbranch_execz .LBB0_1474
	v_lshlrev_b64 v[50:51], 6, v[64:65]
	v_lshl_add_u64 v[50:51], s[68:69], 0, v[50:51]
	v_lshl_add_u64 v[50:51], s[18:19], 2, v[50:51]
	s_lshl_b32 s8, s34, 2
	v_lshl_add_u64 v[50:51], v[50:51], 0, s[8:9]
	s_waitcnt lgkmcnt(0)
	v_add_f32_e32 v48, v48, v49
	global_store_dword v[50:51], v48, off nt
.LBB0_1474:
	s_or_b64 exec, exec, s[20:21]
	v_add_u32_e32 v48, 0x90, v146
	s_waitcnt lgkmcnt(0)
	v_ashrrev_i32_e32 v49, 31, v48
	v_lshlrev_b64 v[50:51], 11, v[48:49]
	v_lshl_add_u64 v[50:51], s[74:75], 0, v[50:51]
	v_lshl_add_u64 v[58:59], v[144:145], 1, v[50:51]
	global_load_dwordx4 v[50:53], v[58:59], off
	global_load_dwordx4 v[54:57], v[58:59], off offset:256
	s_waitcnt vmcnt(1)
	v_lshlrev_b32_e32 v60, 16, v50
	v_and_b32_e32 v61, 0xffff0000, v50
	v_lshlrev_b32_e32 v50, 16, v51
	v_and_b32_e32 v51, 0xffff0000, v51
	v_lshlrev_b32_e32 v62, 16, v52
	v_and_b32_e32 v63, 0xffff0000, v52
	v_lshlrev_b32_e32 v52, 16, v53
	v_and_b32_e32 v53, 0xffff0000, v53
	s_waitcnt vmcnt(0)
	v_lshlrev_b32_e32 v64, 16, v54
	v_and_b32_e32 v65, 0xffff0000, v54
	v_lshlrev_b32_e32 v54, 16, v55
	v_and_b32_e32 v55, 0xffff0000, v55
	v_lshlrev_b32_e32 v66, 16, v56
	v_and_b32_e32 v67, 0xffff0000, v56
	v_lshlrev_b32_e32 v56, 16, v57
	v_and_b32_e32 v57, 0xffff0000, v57
	v_pk_add_f32 v[46:47], v[46:47], v[50:51]
	v_pk_add_f32 v[44:45], v[44:45], v[60:61]
	v_pk_add_f32 v[42:43], v[42:43], v[52:53]
	v_pk_add_f32 v[40:41], v[40:41], v[62:63]
	v_pk_add_f32 v[38:39], v[38:39], v[54:55]
	v_pk_add_f32 v[36:37], v[36:37], v[64:65]
	v_pk_add_f32 v[50:51], v[34:35], v[56:57]
	v_pk_add_f32 v[52:53], v[32:33], v[66:67]
	v_cvt_pk_bf16_f32 v32, v44, v45
	v_cvt_pk_bf16_f32 v33, v46, v47
	v_mul_f32_e32 v34, v45, v45
	v_mul_f32_e32 v35, v47, v47
	v_mul_f32_e32 v45, v41, v41
	v_mul_f32_e32 v47, v43, v43
	v_mul_f32_e32 v54, v37, v37
	v_mul_f32_e32 v55, v39, v39
	v_mul_f32_e32 v56, v53, v53
	v_mul_f32_e32 v57, v51, v51
	v_fmac_f32_e32 v34, v44, v44
	v_fmac_f32_e32 v35, v46, v46
	v_fmac_f32_e32 v45, v40, v40
	v_fmac_f32_e32 v47, v42, v42
	v_fmac_f32_e32 v54, v36, v36
	v_fmac_f32_e32 v55, v38, v38
	v_fmac_f32_e32 v56, v52, v52
	v_fmac_f32_e32 v57, v50, v50
	v_add_f32_e32 v34, v34, v35
	v_add_f32_e32 v35, v45, v47
	v_add_f32_e32 v44, v54, v55
	v_add_f32_e32 v45, v56, v57
	v_add_f32_e32 v34, v34, v35
	v_add_f32_e32 v35, v44, v45
	v_add_f32_e32 v44, v34, v35
	ds_bpermute_b32 v45, v156, v44
	v_cvt_pk_bf16_f32 v34, v40, v41
	v_cvt_pk_bf16_f32 v35, v42, v43
	global_store_dwordx4 v[58:59], v[32:35], off nt
	s_waitcnt lgkmcnt(0)
	s_nop 0
	v_add_f32_e32 v32, v44, v45
	ds_bpermute_b32 v33, v155, v32
	v_cvt_pk_bf16_f32 v34, v36, v37
	v_cvt_pk_bf16_f32 v35, v38, v39
	v_cvt_pk_bf16_f32 v36, v52, v53
	v_cvt_pk_bf16_f32 v37, v50, v51
	global_store_dwordx4 v[58:59], v[34:37], off offset:256 nt
	s_and_saveexec_b64 s[20:21], s[0:1]
	s_cbranch_execz .LBB0_1476
	v_lshlrev_b64 v[34:35], 6, v[48:49]
	v_lshl_add_u64 v[34:35], s[68:69], 0, v[34:35]
	v_lshl_add_u64 v[34:35], s[18:19], 2, v[34:35]
	s_lshl_b32 s8, s34, 2
	v_lshl_add_u64 v[34:35], v[34:35], 0, s[8:9]
	s_waitcnt lgkmcnt(0)
	v_add_f32_e32 v32, v32, v33
	global_store_dword v[34:35], v32, off nt
.LBB0_1476:
	s_or_b64 exec, exec, s[20:21]
	v_add_u32_e32 v32, 0xa0, v146
	s_waitcnt lgkmcnt(0)
	v_ashrrev_i32_e32 v33, 31, v32
	v_lshlrev_b64 v[34:35], 11, v[32:33]
	v_lshl_add_u64 v[34:35], s[74:75], 0, v[34:35]
	v_lshl_add_u64 v[42:43], v[144:145], 1, v[34:35]
	global_load_dwordx4 v[34:37], v[42:43], off
	global_load_dwordx4 v[38:41], v[42:43], off offset:256
	s_waitcnt vmcnt(1)
	v_lshlrev_b32_e32 v44, 16, v34
	v_and_b32_e32 v45, 0xffff0000, v34
	v_lshlrev_b32_e32 v34, 16, v35
	v_and_b32_e32 v35, 0xffff0000, v35
	v_lshlrev_b32_e32 v46, 16, v36
	v_and_b32_e32 v47, 0xffff0000, v36
	v_lshlrev_b32_e32 v36, 16, v37
	v_and_b32_e32 v37, 0xffff0000, v37
	s_waitcnt vmcnt(0)
	v_lshlrev_b32_e32 v48, 16, v38
	v_and_b32_e32 v49, 0xffff0000, v38
	v_lshlrev_b32_e32 v38, 16, v39
	v_and_b32_e32 v39, 0xffff0000, v39
	v_lshlrev_b32_e32 v50, 16, v40
	v_and_b32_e32 v51, 0xffff0000, v40
	v_lshlrev_b32_e32 v40, 16, v41
	v_and_b32_e32 v41, 0xffff0000, v41
	v_pk_add_f32 v[30:31], v[30:31], v[34:35]
	v_pk_add_f32 v[28:29], v[28:29], v[44:45]
	v_pk_add_f32 v[26:27], v[26:27], v[36:37]
	v_pk_add_f32 v[24:25], v[24:25], v[46:47]
	v_pk_add_f32 v[22:23], v[22:23], v[38:39]
	v_pk_add_f32 v[20:21], v[20:21], v[48:49]
	v_pk_add_f32 v[34:35], v[18:19], v[40:41]
	v_pk_add_f32 v[36:37], v[16:17], v[50:51]
	v_cvt_pk_bf16_f32 v16, v28, v29
	v_cvt_pk_bf16_f32 v17, v30, v31
	v_mul_f32_e32 v18, v29, v29
	v_mul_f32_e32 v19, v31, v31
	v_mul_f32_e32 v29, v25, v25
	v_mul_f32_e32 v31, v27, v27
	v_mul_f32_e32 v38, v21, v21
	v_mul_f32_e32 v39, v23, v23
	v_mul_f32_e32 v40, v37, v37
	v_mul_f32_e32 v41, v35, v35
	v_fmac_f32_e32 v18, v28, v28
	v_fmac_f32_e32 v19, v30, v30
	v_fmac_f32_e32 v29, v24, v24
	v_fmac_f32_e32 v31, v26, v26
	v_fmac_f32_e32 v38, v20, v20
	v_fmac_f32_e32 v39, v22, v22
	v_fmac_f32_e32 v40, v36, v36
	v_fmac_f32_e32 v41, v34, v34
	v_add_f32_e32 v18, v18, v19
	v_add_f32_e32 v19, v29, v31
	v_add_f32_e32 v28, v38, v39
	v_add_f32_e32 v29, v40, v41
	v_add_f32_e32 v18, v18, v19
	v_add_f32_e32 v19, v28, v29
	v_add_f32_e32 v28, v18, v19
	ds_bpermute_b32 v29, v156, v28
	v_cvt_pk_bf16_f32 v18, v24, v25
	v_cvt_pk_bf16_f32 v19, v26, v27
	global_store_dwordx4 v[42:43], v[16:19], off nt
	s_waitcnt lgkmcnt(0)
	s_nop 0
	v_add_f32_e32 v16, v28, v29
	ds_bpermute_b32 v17, v155, v16
	v_cvt_pk_bf16_f32 v18, v20, v21
	v_cvt_pk_bf16_f32 v19, v22, v23
	v_cvt_pk_bf16_f32 v20, v36, v37
	v_cvt_pk_bf16_f32 v21, v34, v35
	global_store_dwordx4 v[42:43], v[18:21], off offset:256 nt
	s_and_saveexec_b64 s[20:21], s[0:1]
	s_cbranch_execz .LBB0_1478
	v_lshlrev_b64 v[18:19], 6, v[32:33]
	v_lshl_add_u64 v[18:19], s[68:69], 0, v[18:19]
	v_lshl_add_u64 v[18:19], s[18:19], 2, v[18:19]
	s_lshl_b32 s8, s34, 2
	v_lshl_add_u64 v[18:19], v[18:19], 0, s[8:9]
	s_waitcnt lgkmcnt(0)
	v_add_f32_e32 v16, v16, v17
	global_store_dword v[18:19], v16, off nt
.LBB0_1478:
	s_or_b64 exec, exec, s[20:21]
	v_add_u32_e32 v16, 0xb0, v146
	s_waitcnt lgkmcnt(0)
	v_ashrrev_i32_e32 v17, 31, v16
	v_lshlrev_b64 v[18:19], 11, v[16:17]
	v_lshl_add_u64 v[18:19], s[74:75], 0, v[18:19]
	v_lshl_add_u64 v[26:27], v[144:145], 1, v[18:19]
	global_load_dwordx4 v[18:21], v[26:27], off
	global_load_dwordx4 v[22:25], v[26:27], off offset:256
	s_waitcnt vmcnt(1)
	v_lshlrev_b32_e32 v28, 16, v18
	v_and_b32_e32 v29, 0xffff0000, v18
	v_lshlrev_b32_e32 v18, 16, v19
	v_and_b32_e32 v19, 0xffff0000, v19
	v_lshlrev_b32_e32 v30, 16, v20
	v_and_b32_e32 v31, 0xffff0000, v20
	v_lshlrev_b32_e32 v20, 16, v21
	v_and_b32_e32 v21, 0xffff0000, v21
	s_waitcnt vmcnt(0)
	v_lshlrev_b32_e32 v32, 16, v22
	v_and_b32_e32 v33, 0xffff0000, v22
	v_lshlrev_b32_e32 v22, 16, v23
	v_and_b32_e32 v23, 0xffff0000, v23
	v_lshlrev_b32_e32 v34, 16, v24
	v_and_b32_e32 v35, 0xffff0000, v24
	v_lshlrev_b32_e32 v24, 16, v25
	v_and_b32_e32 v25, 0xffff0000, v25
	v_pk_add_f32 v[14:15], v[14:15], v[18:19]
	v_pk_add_f32 v[12:13], v[12:13], v[28:29]
	v_pk_add_f32 v[10:11], v[10:11], v[20:21]
	v_pk_add_f32 v[8:9], v[8:9], v[30:31]
	v_pk_add_f32 v[6:7], v[6:7], v[22:23]
	v_pk_add_f32 v[4:5], v[4:5], v[32:33]
	v_pk_add_f32 v[18:19], v[2:3], v[24:25]
	v_pk_add_f32 v[20:21], v[0:1], v[34:35]
	v_cvt_pk_bf16_f32 v0, v12, v13
	v_cvt_pk_bf16_f32 v1, v14, v15
	v_mul_f32_e32 v2, v13, v13
	v_mul_f32_e32 v3, v15, v15
	v_mul_f32_e32 v13, v9, v9
	v_mul_f32_e32 v15, v11, v11
	v_mul_f32_e32 v22, v5, v5
	v_mul_f32_e32 v23, v7, v7
	v_mul_f32_e32 v24, v21, v21
	v_mul_f32_e32 v25, v19, v19
	v_fmac_f32_e32 v2, v12, v12
	v_fmac_f32_e32 v3, v14, v14
	v_fmac_f32_e32 v13, v8, v8
	v_fmac_f32_e32 v15, v10, v10
	v_fmac_f32_e32 v22, v4, v4
	v_fmac_f32_e32 v23, v6, v6
	v_fmac_f32_e32 v24, v20, v20
	v_fmac_f32_e32 v25, v18, v18
	v_add_f32_e32 v2, v2, v3
	v_add_f32_e32 v3, v13, v15
	v_add_f32_e32 v12, v22, v23
	v_add_f32_e32 v13, v24, v25
	v_add_f32_e32 v2, v2, v3
	v_add_f32_e32 v3, v12, v13
	v_add_f32_e32 v12, v2, v3
	ds_bpermute_b32 v13, v156, v12
	v_cvt_pk_bf16_f32 v2, v8, v9
	v_cvt_pk_bf16_f32 v3, v10, v11
	global_store_dwordx4 v[26:27], v[0:3], off nt
	s_waitcnt lgkmcnt(0)
	s_nop 0
	v_add_f32_e32 v0, v12, v13
	ds_bpermute_b32 v1, v155, v0
	v_cvt_pk_bf16_f32 v2, v4, v5
	v_cvt_pk_bf16_f32 v3, v6, v7
	v_cvt_pk_bf16_f32 v4, v20, v21
	v_cvt_pk_bf16_f32 v5, v18, v19
	global_store_dwordx4 v[26:27], v[2:5], off offset:256 nt
	s_and_saveexec_b64 s[20:21], s[0:1]
	s_cbranch_execz .LBB0_1480
	v_lshlrev_b64 v[2:3], 6, v[16:17]
	v_lshl_add_u64 v[2:3], s[68:69], 0, v[2:3]
	v_lshl_add_u64 v[2:3], s[18:19], 2, v[2:3]
	s_lshl_b32 s8, s34, 2
	v_lshl_add_u64 v[2:3], v[2:3], 0, s[8:9]
	s_waitcnt lgkmcnt(0)
	v_add_f32_e32 v0, v0, v1
	global_store_dword v[2:3], v0, off nt
